# FFN-in f0 loop: 64-MFMA blocks, all LDS-DMA staging moved to load segments (leading half stages B/A0 pieces of both halves, trailing half the A1 pieces)
# speedup vs baseline: 1.0047x; 1.0047x over previous
; #define PG8_STAGE(bufoff, gbase, voff) do { _Pragma("unroll") for (int _i = 0; _i < 2; ++_i) \
;         __builtin_amdgcn_global_load_lds((const unsigned*)((const char*)(gbase) + (voff)[_i]), (PG8_LAS unsigned*)(lds + (bufoff) + ldsw + _i * 8192), 16, 0, 0); } while (0)
; #define PG8_LDA(dst, b, h) do { _Pragma("unroll") for (int m = 0; m < 4; ++m) _Pragma("unroll") for (int k = 0; k < 2; ++k) dst[m][k] = *(const PG8_LAS bf16x8*)(lds + PG8_SA(b, h) + aoff + m * 2048 + k * 1024); } while (0)
; #define PG8_LDB(dst, b, h) do { _Pragma("unroll") for (int n = 0; n < 2; ++n) _Pragma("unroll") for (int k = 0; k < 2; ++k) dst[n][k] = *(const PG8_LAS bf16x8*)(lds + PG8_SB(b, h) + boff + n * 2048 + k * 1024); } while (0)
; template <class Epi, class Sched, bool ALIGN_EPI = false, bool SP2 = false>
; __device__ __forceinline__ void gemm_phase(PG8_LAS unsigned char* lds, const Gemm g, const Sched& S, const Epi& E) {
;     ...
;         for (int t = 0; t < nt; t += 2) {
;             const bool last = (t == nt - 2);
;             const char* a1 = cA + (size_t)(t + 1) * kstA;
;             const char* a2 = last ? nA : cA + (size_t)(t + 2) * kstA; const char* b2 = last ? nB : cB + (size_t)(t + 2) * kstep;
;             const char* a3 = a2 + kstA; const char* b3 = b2 + kstep;
;             if (last && has_next) S.a_ready(nxt);
;             if constexpr (SP2) {
;             PG8_LDB(B0, 0, 0); PG8_LDB(B1, 0, 1); PG8_SCHED; PG8_LDA(At, 0, 0); PG8_STAGE(PG8_SA(1, 1), a1 + hstepA, voffA);
;             PG8_WAIT_V(8); PG8_WAIT_L(0); PG8_BAR; PG8_MMA(0, 0, At, B0); PG8_MMA(0, 1, At, B1); PG8_BAR; PG8_SCHED;
;             PG8_LDA(At, 0, 1); PG8_STAGE(PG8_SB(0, 0), b2, voffB); PG8_STAGE(PG8_SB(0, 1), b2 + hstepB, voffB); PG8_STAGE(PG8_SA(0, 0), a2, voffA);
;             PG8_WAIT_V(8); PG8_WAIT_L(0); PG8_BAR; PG8_MMA(1, 0, At, B0); PG8_MMA(1, 1, At, B1); PG8_BAR; PG8_SCHED;
;             PG8_LDB(B0, 1, 0); PG8_LDB(B1, 1, 1); PG8_SCHED; PG8_LDA(At, 1, 0); PG8_STAGE(PG8_SA(0, 1), a2 + hstepA, voffA);
;             PG8_WAIT_V(8); PG8_WAIT_L(0); PG8_BAR; PG8_MMA(0, 0, At, B0); PG8_MMA(0, 1, At, B1); PG8_BAR; PG8_SCHED;
;             PG8_LDA(At, 1, 1); PG8_STAGE(PG8_SB(1, 0), b3, voffB); PG8_STAGE(PG8_SB(1, 1), b3 + hstepB, voffB); PG8_STAGE(PG8_SA(1, 0), a3, voffA);
;             PG8_WAIT_V(8); PG8_WAIT_L(0); PG8_BAR; PG8_MMA(1, 0, At, B0); PG8_MMA(1, 1, At, B1); PG8_BAR; PG8_SCHED;
.LBB0_300:
	s_and_b64 vcc, exec, s[38:39]
	s_cbranch_vccz .Lmy_m64_0_w1_entry
	v_mov_b32_e32 v234, 0x20000
	v_mov_b32_e32 v235, 0
	s_branch .Lmy_m64_0_w0_first
.Lmy_m64_0_w0_top:
	s_add_i32 s58, s62, s3
	v_lshl_add_u64 v[222:223], v[222:223], 0, s[36:37]
	s_mov_b32 m0, s58
	s_nop 0
	global_load_lds_dwordx4 v[222:223], off
	v_lshl_add_u64 v[232:233], v[222:223], 0, v[234:235]
	s_bitset1_b32 m0, 12
	s_nop 0
	global_load_lds_dwordx4 v[232:233], off
	s_add_i32 m0, s58, 0x2000
	s_add_u32 s56, s56, 0x80080
	v_lshl_add_u64 v[222:223], v[224:225], 0, s[36:37]
	s_addc_u32 s57, s57, 0
	s_add_i32 s58, s63, s3
	global_load_lds_dwordx4 v[222:223], off
	v_lshl_add_u64 v[232:233], v[222:223], 0, v[234:235]
	s_bitset1_b32 m0, 12
	s_nop 0
	global_load_lds_dwordx4 v[232:233], off
	v_lshl_add_u64 v[222:223], s[56:57], 0, v[130:131]
	s_mov_b32 m0, s58
	s_nop 0
	global_load_lds_dwordx4 v[222:223], off
	v_lshl_add_u64 v[232:233], v[222:223], 0, v[234:235]
	s_bitset1_b32 m0, 12
	s_nop 0
	global_load_lds_dwordx4 v[232:233], off
	v_lshl_add_u64 v[222:223], s[56:57], 0, v[134:135]
	s_add_i32 m0, s58, 0x2000
	s_nop 0
	global_load_lds_dwordx4 v[222:223], off
	v_lshl_add_u64 v[232:233], v[222:223], 0, v[234:235]
	s_bitset1_b32 m0, 12
	s_nop 0
	global_load_lds_dwordx4 v[232:233], off
	v_lshl_add_u64 v[222:223], v[226:227], 0, s[36:37]
	s_mov_b32 m0, s44
	s_nop 0
	global_load_lds_dwordx4 v[222:223], off
	v_lshl_add_u64 v[232:233], v[222:223], 0, v[234:235]
	s_bitset1_b32 m0, 12
	s_nop 0
	global_load_lds_dwordx4 v[232:233], off
	v_lshl_add_u64 v[222:223], v[228:229], 0, s[36:37]
	s_mov_b32 m0, s45
	s_nop 0
	global_load_lds_dwordx4 v[222:223], off
	v_lshl_add_u64 v[232:233], v[222:223], 0, v[234:235]
	s_bitset1_b32 m0, 12
	s_nop 0
	global_load_lds_dwordx4 v[232:233], off
.Lmy_m64_0_w0_first:
	s_add_u32 s56, s50, 0xfff80080
	s_addc_u32 s57, s51, -1
	s_cmp_eq_u32 s61, 28
	s_cselect_b32 s59, s4, s57
	s_cselect_b32 s58, s5, s56
	s_cselect_b32 s57, s12, s43
	s_cselect_b32 s56, s13, s41
	ds_read_b128 v[156:159], v152
	ds_read_b128 v[160:163], v152 offset:1024
	ds_read_b128 v[164:167], v152 offset:2048
	ds_read_b128 v[168:171], v152 offset:3072
	ds_read_b128 v[172:175], v153
	ds_read_b128 v[176:179], v153 offset:1024
	ds_read_b128 v[180:183], v153 offset:2048
	ds_read_b128 v[186:189], v153 offset:3072
	ds_read_b128 v[190:193], v154
	ds_read_b128 v[194:197], v154 offset:1024
	ds_read_b128 v[198:201], v154 offset:2048
	ds_read_b128 v[202:205], v154 offset:3072
	ds_read_b128 v[206:209], v154 offset:4096
	ds_read_b128 v[210:213], v154 offset:5120
	ds_read_b128 v[214:217], v154 offset:6144
	ds_read_b128 v[218:221], v154 offset:7168
	s_waitcnt lgkmcnt(0)
	s_setprio 1
	s_barrier
	v_mfma_f32_16x16x32_bf16 v[124:127], v[156:159], v[190:193], v[124:127]
	v_mfma_f32_16x16x32_bf16 v[120:123], v[164:167], v[190:193], v[120:123]
	v_mfma_f32_16x16x32_bf16 v[116:119], v[172:175], v[190:193], v[116:119]
	v_mfma_f32_16x16x32_bf16 v[112:115], v[180:183], v[190:193], v[112:115]
	v_mfma_f32_16x16x32_bf16 v[124:127], v[160:163], v[194:197], v[124:127]
	v_mfma_f32_16x16x32_bf16 v[120:123], v[168:171], v[194:197], v[120:123]
	v_mfma_f32_16x16x32_bf16 v[116:119], v[176:179], v[194:197], v[116:119]
	v_mfma_f32_16x16x32_bf16 v[112:115], v[186:189], v[194:197], v[112:115]
	ds_read_b128 v[190:193], v154 offset:16384
	ds_read_b128 v[194:197], v154 offset:17408
	v_mfma_f32_16x16x32_bf16 v[108:111], v[156:159], v[198:201], v[108:111]
	v_mfma_f32_16x16x32_bf16 v[104:107], v[164:167], v[198:201], v[104:107]
	v_mfma_f32_16x16x32_bf16 v[100:103], v[172:175], v[198:201], v[100:103]
	v_mfma_f32_16x16x32_bf16 v[96:99], v[180:183], v[198:201], v[96:99]
	v_mfma_f32_16x16x32_bf16 v[108:111], v[160:163], v[202:205], v[108:111]
	v_mfma_f32_16x16x32_bf16 v[104:107], v[168:171], v[202:205], v[104:107]
	v_mfma_f32_16x16x32_bf16 v[100:103], v[176:179], v[202:205], v[100:103]
	v_mfma_f32_16x16x32_bf16 v[96:99], v[186:189], v[202:205], v[96:99]
	ds_read_b128 v[198:201], v154 offset:18432
	ds_read_b128 v[202:205], v154 offset:19456
	v_mfma_f32_16x16x32_bf16 v[92:95], v[156:159], v[206:209], v[92:95]
	v_mfma_f32_16x16x32_bf16 v[88:91], v[164:167], v[206:209], v[88:91]
	v_mfma_f32_16x16x32_bf16 v[84:87], v[172:175], v[206:209], v[84:87]
	v_mfma_f32_16x16x32_bf16 v[80:83], v[180:183], v[206:209], v[80:83]
	v_mfma_f32_16x16x32_bf16 v[92:95], v[160:163], v[210:213], v[92:95]
	v_mfma_f32_16x16x32_bf16 v[88:91], v[168:171], v[210:213], v[88:91]
	v_mfma_f32_16x16x32_bf16 v[84:87], v[176:179], v[210:213], v[84:87]
	v_mfma_f32_16x16x32_bf16 v[80:83], v[186:189], v[210:213], v[80:83]
	ds_read_b128 v[206:209], v154 offset:20480
	ds_read_b128 v[210:213], v154 offset:21504
	v_mfma_f32_16x16x32_bf16 v[76:79], v[156:159], v[214:217], v[76:79]
	v_mfma_f32_16x16x32_bf16 v[72:75], v[164:167], v[214:217], v[72:75]
	v_mfma_f32_16x16x32_bf16 v[68:71], v[172:175], v[214:217], v[68:71]
	v_mfma_f32_16x16x32_bf16 v[64:67], v[180:183], v[214:217], v[64:67]
	v_mfma_f32_16x16x32_bf16 v[76:79], v[160:163], v[218:221], v[76:79]
	v_mfma_f32_16x16x32_bf16 v[72:75], v[168:171], v[218:221], v[72:75]
	v_mfma_f32_16x16x32_bf16 v[68:71], v[176:179], v[218:221], v[68:71]
	v_mfma_f32_16x16x32_bf16 v[64:67], v[186:189], v[218:221], v[64:67]
	ds_read_b128 v[214:217], v154 offset:22528
	ds_read_b128 v[218:221], v154 offset:23552
	s_waitcnt lgkmcnt(6)
	v_mfma_f32_16x16x32_bf16 v[60:63], v[156:159], v[190:193], v[60:63]
	v_mfma_f32_16x16x32_bf16 v[56:59], v[164:167], v[190:193], v[56:59]
	v_mfma_f32_16x16x32_bf16 v[52:55], v[172:175], v[190:193], v[52:55]
	v_mfma_f32_16x16x32_bf16 v[48:51], v[180:183], v[190:193], v[48:51]
	v_mfma_f32_16x16x32_bf16 v[60:63], v[160:163], v[194:197], v[60:63]
	v_mfma_f32_16x16x32_bf16 v[56:59], v[168:171], v[194:197], v[56:59]
	v_mfma_f32_16x16x32_bf16 v[52:55], v[176:179], v[194:197], v[52:55]
	v_mfma_f32_16x16x32_bf16 v[48:51], v[186:189], v[194:197], v[48:51]
	s_waitcnt lgkmcnt(4)
; #define PG8_STAGE(bufoff, gbase, voff) do { _Pragma("unroll") for (int _i = 0; _i < 2; ++_i) \
;         __builtin_amdgcn_global_load_lds((const unsigned*)((const char*)(gbase) + (voff)[_i]), (PG8_LAS unsigned*)(lds + (bufoff) + ldsw + _i * 8192), 16, 0, 0); } while (0)
; #define PG8_LDA(dst, b, h) do { _Pragma("unroll") for (int m = 0; m < 4; ++m) _Pragma("unroll") for (int k = 0; k < 2; ++k) dst[m][k] = *(const PG8_LAS bf16x8*)(lds + PG8_SA(b, h) + aoff + m * 2048 + k * 1024); } while (0)
; #define PG8_LDB(dst, b, h) do { _Pragma("unroll") for (int n = 0; n < 2; ++n) _Pragma("unroll") for (int k = 0; k < 2; ++k) dst[n][k] = *(const PG8_LAS bf16x8*)(lds + PG8_SB(b, h) + boff + n * 2048 + k * 1024); } while (0)
; #define PG8_MMA(ai, bj, At, Bt) do { __builtin_amdgcn_s_setprio(1); _Pragma("unroll") for (int m = 0; m < 4; ++m) _Pragma("unroll") for (int n = 0; n < 2; ++n) _Pragma("unroll") for (int k = 0; k < 2; ++k) \
;         acc[ai][bj][m][n] = __builtin_amdgcn_mfma_f32_16x16x32_bf16(Bt[n][k], At[m][k], acc[ai][bj][m][n], 0, 0, 0); __builtin_amdgcn_s_setprio(0); } while (0)
; template <class Epi, class Sched, bool ALIGN_EPI = false, bool SP2 = false>
; __device__ __forceinline__ void gemm_phase(PG8_LAS unsigned char* lds, const Gemm g, const Sched& S, const Epi& E) {
;     ...
;             if constexpr (SP2) {
;             PG8_LDB(B0, 0, 0); PG8_LDB(B1, 0, 1); PG8_SCHED; PG8_LDA(At, 0, 0); PG8_STAGE(PG8_SA(1, 1), a1 + hstepA, voffA);
;             PG8_WAIT_V(8); PG8_WAIT_L(0); PG8_BAR; PG8_MMA(0, 0, At, B0); PG8_MMA(0, 1, At, B1); PG8_BAR; PG8_SCHED;
;             PG8_LDA(At, 0, 1); PG8_STAGE(PG8_SB(0, 0), b2, voffB); PG8_STAGE(PG8_SB(0, 1), b2 + hstepB, voffB); PG8_STAGE(PG8_SA(0, 0), a2, voffA);
;             PG8_WAIT_V(8); PG8_WAIT_L(0); PG8_BAR; PG8_MMA(1, 0, At, B0); PG8_MMA(1, 1, At, B1); PG8_BAR; PG8_SCHED;
;             PG8_LDB(B0, 1, 0); PG8_LDB(B1, 1, 1); PG8_SCHED; PG8_LDA(At, 1, 0); PG8_STAGE(PG8_SA(0, 1), a2 + hstepA, voffA);
;             PG8_WAIT_V(8); PG8_WAIT_L(0); PG8_BAR; PG8_MMA(0, 0, At, B0); PG8_MMA(0, 1, At, B1); PG8_BAR; PG8_SCHED;
;             PG8_LDA(At, 1, 1); PG8_STAGE(PG8_SB(1, 0), b3, voffB); PG8_STAGE(PG8_SB(1, 1), b3 + hstepB, voffB); PG8_STAGE(PG8_SA(1, 0), a3, voffA);
;             PG8_WAIT_V(8); PG8_WAIT_L(0); PG8_BAR; PG8_MMA(1, 0, At, B0); PG8_MMA(1, 1, At, B1); PG8_BAR; PG8_SCHED;
	v_mfma_f32_16x16x32_bf16 v[44:47], v[156:159], v[198:201], v[44:47]
	v_mfma_f32_16x16x32_bf16 v[40:43], v[164:167], v[198:201], v[40:43]
	v_mfma_f32_16x16x32_bf16 v[36:39], v[172:175], v[198:201], v[36:39]
	v_mfma_f32_16x16x32_bf16 v[32:35], v[180:183], v[198:201], v[32:35]
	v_mfma_f32_16x16x32_bf16 v[44:47], v[160:163], v[202:205], v[44:47]
	v_mfma_f32_16x16x32_bf16 v[40:43], v[168:171], v[202:205], v[40:43]
	v_mfma_f32_16x16x32_bf16 v[36:39], v[176:179], v[202:205], v[36:39]
	v_mfma_f32_16x16x32_bf16 v[32:35], v[186:189], v[202:205], v[32:35]
	s_waitcnt lgkmcnt(2)
	v_mfma_f32_16x16x32_bf16 v[28:31], v[156:159], v[206:209], v[28:31]
	v_mfma_f32_16x16x32_bf16 v[24:27], v[164:167], v[206:209], v[24:27]
	v_mfma_f32_16x16x32_bf16 v[20:23], v[172:175], v[206:209], v[20:23]
	v_mfma_f32_16x16x32_bf16 v[16:19], v[180:183], v[206:209], v[16:19]
	v_mfma_f32_16x16x32_bf16 v[28:31], v[160:163], v[210:213], v[28:31]
	v_mfma_f32_16x16x32_bf16 v[24:27], v[168:171], v[210:213], v[24:27]
	v_mfma_f32_16x16x32_bf16 v[20:23], v[176:179], v[210:213], v[20:23]
	v_mfma_f32_16x16x32_bf16 v[16:19], v[186:189], v[210:213], v[16:19]
	s_waitcnt lgkmcnt(0)
	v_mfma_f32_16x16x32_bf16 v[12:15], v[156:159], v[214:217], v[12:15]
	v_mfma_f32_16x16x32_bf16 v[8:11], v[164:167], v[214:217], v[8:11]
	v_mfma_f32_16x16x32_bf16 v[4:7], v[172:175], v[214:217], v[4:7]
	v_mfma_f32_16x16x32_bf16 v[0:3], v[180:183], v[214:217], v[0:3]
	v_mfma_f32_16x16x32_bf16 v[12:15], v[160:163], v[218:221], v[12:15]
	v_mfma_f32_16x16x32_bf16 v[8:11], v[168:171], v[218:221], v[8:11]
	v_mfma_f32_16x16x32_bf16 v[4:7], v[176:179], v[218:221], v[4:7]
	v_mfma_f32_16x16x32_bf16 v[0:3], v[186:189], v[218:221], v[0:3]
	s_waitcnt vmcnt(0)
	s_barrier
	s_setprio 0
	s_add_i32 s62, s53, s3
	v_lshl_add_u64 v[222:223], s[56:57], 0, v[130:131]
	s_mov_b32 m0, s62
	s_nop 0
	global_load_lds_dwordx4 v[222:223], off
	v_lshl_add_u64 v[232:233], v[222:223], 0, v[234:235]
	s_bitset1_b32 m0, 12
	s_nop 0
	global_load_lds_dwordx4 v[232:233], off
	s_add_i32 m0, s62, 0x2000
	s_add_u32 s62, s56, 0x80000
	v_lshl_add_u64 v[224:225], s[56:57], 0, v[134:135]
	s_addc_u32 s63, s57, 0
	s_add_i32 s64, s55, s3
	global_load_lds_dwordx4 v[224:225], off
	v_lshl_add_u64 v[232:233], v[224:225], 0, v[234:235]
	s_bitset1_b32 m0, 12
	s_nop 0
	global_load_lds_dwordx4 v[232:233], off
	v_lshl_add_u64 v[226:227], s[62:63], 0, v[130:131]
	s_mov_b32 m0, s64
	v_lshl_add_u64 v[228:229], s[58:59], 0, v[132:133]
	global_load_lds_dwordx4 v[226:227], off
	v_lshl_add_u64 v[232:233], v[226:227], 0, v[234:235]
	s_bitset1_b32 m0, 12
	s_nop 0
	global_load_lds_dwordx4 v[232:233], off
	v_lshl_add_u64 v[226:227], s[62:63], 0, v[134:135]
	s_add_i32 m0, s64, 0x2000
	s_nop 0
	global_load_lds_dwordx4 v[226:227], off
	v_lshl_add_u64 v[232:233], v[226:227], 0, v[234:235]
	s_bitset1_b32 m0, 12
	s_nop 0
	global_load_lds_dwordx4 v[232:233], off
	v_lshl_add_u64 v[226:227], s[58:59], 0, v[128:129]
	s_mov_b32 m0, s6
	s_nop 0
	global_load_lds_dwordx4 v[226:227], off
	v_lshl_add_u64 v[232:233], v[226:227], 0, v[234:235]
	s_bitset1_b32 m0, 12
	s_nop 0
	global_load_lds_dwordx4 v[232:233], off
	s_mov_b32 m0, s7
	s_nop 0
	global_load_lds_dwordx4 v[228:229], off
	v_lshl_add_u64 v[232:233], v[228:229], 0, v[234:235]
	s_bitset1_b32 m0, 12
	s_nop 0
	global_load_lds_dwordx4 v[232:233], off
	s_add_i32 s62, 0, 0x18000
	v_add_u32_e32 v155, s62, v150
	s_add_i32 s63, 0, 0x1c000
	ds_read_b128 v[156:159], v155
	ds_read_b128 v[160:163], v155 offset:1024
	ds_read_b128 v[164:167], v155 offset:2048
	ds_read_b128 v[168:171], v155 offset:3072
	v_add_u32_e32 v155, s63, v150
	ds_read_b128 v[172:175], v155
	ds_read_b128 v[176:179], v155 offset:1024
	ds_read_b128 v[180:183], v155 offset:2048
	ds_read_b128 v[186:189], v155 offset:3072
	ds_read_b128 v[190:193], v154 offset:32768
	ds_read_b128 v[194:197], v154 offset:33792
	ds_read_b128 v[198:201], v154 offset:34816
	ds_read_b128 v[202:205], v154 offset:35840
	ds_read_b128 v[206:209], v154 offset:36864
	ds_read_b128 v[210:213], v154 offset:37888
	ds_read_b128 v[214:217], v154 offset:38912
	ds_read_b128 v[218:221], v154 offset:39936
	s_waitcnt lgkmcnt(0)
	s_setprio 1
	s_barrier
	v_mfma_f32_16x16x32_bf16 v[124:127], v[156:159], v[190:193], v[124:127]
	v_mfma_f32_16x16x32_bf16 v[120:123], v[164:167], v[190:193], v[120:123]
	v_mfma_f32_16x16x32_bf16 v[116:119], v[172:175], v[190:193], v[116:119]
	v_mfma_f32_16x16x32_bf16 v[112:115], v[180:183], v[190:193], v[112:115]
	v_mfma_f32_16x16x32_bf16 v[124:127], v[160:163], v[194:197], v[124:127]
	v_mfma_f32_16x16x32_bf16 v[120:123], v[168:171], v[194:197], v[120:123]
	v_mfma_f32_16x16x32_bf16 v[116:119], v[176:179], v[194:197], v[116:119]
	v_mfma_f32_16x16x32_bf16 v[112:115], v[186:189], v[194:197], v[112:115]
	ds_read_b128 v[190:193], v154 offset:49152
	ds_read_b128 v[194:197], v154 offset:50176
	v_mfma_f32_16x16x32_bf16 v[108:111], v[156:159], v[198:201], v[108:111]
	v_mfma_f32_16x16x32_bf16 v[104:107], v[164:167], v[198:201], v[104:107]
	v_mfma_f32_16x16x32_bf16 v[100:103], v[172:175], v[198:201], v[100:103]
	v_mfma_f32_16x16x32_bf16 v[96:99], v[180:183], v[198:201], v[96:99]
	v_mfma_f32_16x16x32_bf16 v[108:111], v[160:163], v[202:205], v[108:111]
	v_mfma_f32_16x16x32_bf16 v[104:107], v[168:171], v[202:205], v[104:107]
	v_mfma_f32_16x16x32_bf16 v[100:103], v[176:179], v[202:205], v[100:103]
	v_mfma_f32_16x16x32_bf16 v[96:99], v[186:189], v[202:205], v[96:99]
	ds_read_b128 v[198:201], v154 offset:51200
	ds_read_b128 v[202:205], v154 offset:52224
	v_mfma_f32_16x16x32_bf16 v[92:95], v[156:159], v[206:209], v[92:95]
	v_mfma_f32_16x16x32_bf16 v[88:91], v[164:167], v[206:209], v[88:91]
	v_mfma_f32_16x16x32_bf16 v[84:87], v[172:175], v[206:209], v[84:87]
	v_mfma_f32_16x16x32_bf16 v[80:83], v[180:183], v[206:209], v[80:83]
	v_mfma_f32_16x16x32_bf16 v[92:95], v[160:163], v[210:213], v[92:95]
	v_mfma_f32_16x16x32_bf16 v[88:91], v[168:171], v[210:213], v[88:91]
	v_mfma_f32_16x16x32_bf16 v[84:87], v[176:179], v[210:213], v[84:87]
	v_mfma_f32_16x16x32_bf16 v[80:83], v[186:189], v[210:213], v[80:83]
	ds_read_b128 v[206:209], v154 offset:53248
	ds_read_b128 v[210:213], v154 offset:54272
	v_mfma_f32_16x16x32_bf16 v[76:79], v[156:159], v[214:217], v[76:79]
	v_mfma_f32_16x16x32_bf16 v[72:75], v[164:167], v[214:217], v[72:75]
	v_mfma_f32_16x16x32_bf16 v[68:71], v[172:175], v[214:217], v[68:71]
	v_mfma_f32_16x16x32_bf16 v[64:67], v[180:183], v[214:217], v[64:67]
	v_mfma_f32_16x16x32_bf16 v[76:79], v[160:163], v[218:221], v[76:79]
	v_mfma_f32_16x16x32_bf16 v[72:75], v[168:171], v[218:221], v[72:75]
	v_mfma_f32_16x16x32_bf16 v[68:71], v[176:179], v[218:221], v[68:71]
	v_mfma_f32_16x16x32_bf16 v[64:67], v[186:189], v[218:221], v[64:67]
	ds_read_b128 v[214:217], v154 offset:55296
	ds_read_b128 v[218:221], v154 offset:56320
	s_waitcnt lgkmcnt(6)
; #define PG8_STAGE(bufoff, gbase, voff) do { _Pragma("unroll") for (int _i = 0; _i < 2; ++_i) \
;         __builtin_amdgcn_global_load_lds((const unsigned*)((const char*)(gbase) + (voff)[_i]), (PG8_LAS unsigned*)(lds + (bufoff) + ldsw + _i * 8192), 16, 0, 0); } while (0)
; #define PG8_LDA(dst, b, h) do { _Pragma("unroll") for (int m = 0; m < 4; ++m) _Pragma("unroll") for (int k = 0; k < 2; ++k) dst[m][k] = *(const PG8_LAS bf16x8*)(lds + PG8_SA(b, h) + aoff + m * 2048 + k * 1024); } while (0)
; #define PG8_LDB(dst, b, h) do { _Pragma("unroll") for (int n = 0; n < 2; ++n) _Pragma("unroll") for (int k = 0; k < 2; ++k) dst[n][k] = *(const PG8_LAS bf16x8*)(lds + PG8_SB(b, h) + boff + n * 2048 + k * 1024); } while (0)
; template <class Epi, class Sched, bool ALIGN_EPI = false, bool SP2 = false>
; __device__ __forceinline__ void gemm_phase(PG8_LAS unsigned char* lds, const Gemm g, const Sched& S, const Epi& E) {
;     ...
;         for (int t = 0; t < nt; t += 2) {
;             const bool last = (t == nt - 2);
;             const char* a1 = cA + (size_t)(t + 1) * kstA;
;             const char* a2 = last ? nA : cA + (size_t)(t + 2) * kstA; const char* b2 = last ? nB : cB + (size_t)(t + 2) * kstep;
;             const char* a3 = a2 + kstA; const char* b3 = b2 + kstep;
;             if (last && has_next) S.a_ready(nxt);
;             if constexpr (SP2) {
;             PG8_LDB(B0, 0, 0); PG8_LDB(B1, 0, 1); PG8_SCHED; PG8_LDA(At, 0, 0); PG8_STAGE(PG8_SA(1, 1), a1 + hstepA, voffA);
;             PG8_WAIT_V(8); PG8_WAIT_L(0); PG8_BAR; PG8_MMA(0, 0, At, B0); PG8_MMA(0, 1, At, B1); PG8_BAR; PG8_SCHED;
;             PG8_LDA(At, 0, 1); PG8_STAGE(PG8_SB(0, 0), b2, voffB); PG8_STAGE(PG8_SB(0, 1), b2 + hstepB, voffB); PG8_STAGE(PG8_SA(0, 0), a2, voffA);
;             PG8_WAIT_V(8); PG8_WAIT_L(0); PG8_BAR; PG8_MMA(1, 0, At, B0); PG8_MMA(1, 1, At, B1); PG8_BAR; PG8_SCHED;
;             PG8_LDB(B0, 1, 0); PG8_LDB(B1, 1, 1); PG8_SCHED; PG8_LDA(At, 1, 0); PG8_STAGE(PG8_SA(0, 1), a2 + hstepA, voffA);
;             PG8_WAIT_V(8); PG8_WAIT_L(0); PG8_BAR; PG8_MMA(0, 0, At, B0); PG8_MMA(0, 1, At, B1); PG8_BAR; PG8_SCHED;
;             PG8_LDA(At, 1, 1); PG8_STAGE(PG8_SB(1, 0), b3, voffB); PG8_STAGE(PG8_SB(1, 1), b3 + hstepB, voffB); PG8_STAGE(PG8_SA(1, 0), a3, voffA);
;             PG8_WAIT_V(8); PG8_WAIT_L(0); PG8_BAR; PG8_MMA(1, 0, At, B0); PG8_MMA(1, 1, At, B1); PG8_BAR; PG8_SCHED;
	v_mfma_f32_16x16x32_bf16 v[60:63], v[156:159], v[190:193], v[60:63]
	v_mfma_f32_16x16x32_bf16 v[56:59], v[164:167], v[190:193], v[56:59]
	v_mfma_f32_16x16x32_bf16 v[52:55], v[172:175], v[190:193], v[52:55]
	v_mfma_f32_16x16x32_bf16 v[48:51], v[180:183], v[190:193], v[48:51]
	v_mfma_f32_16x16x32_bf16 v[60:63], v[160:163], v[194:197], v[60:63]
	v_mfma_f32_16x16x32_bf16 v[56:59], v[168:171], v[194:197], v[56:59]
	v_mfma_f32_16x16x32_bf16 v[52:55], v[176:179], v[194:197], v[52:55]
	v_mfma_f32_16x16x32_bf16 v[48:51], v[186:189], v[194:197], v[48:51]
	s_waitcnt lgkmcnt(4)
	v_mfma_f32_16x16x32_bf16 v[44:47], v[156:159], v[198:201], v[44:47]
	v_mfma_f32_16x16x32_bf16 v[40:43], v[164:167], v[198:201], v[40:43]
	v_mfma_f32_16x16x32_bf16 v[36:39], v[172:175], v[198:201], v[36:39]
	v_mfma_f32_16x16x32_bf16 v[32:35], v[180:183], v[198:201], v[32:35]
	v_mfma_f32_16x16x32_bf16 v[44:47], v[160:163], v[202:205], v[44:47]
	v_mfma_f32_16x16x32_bf16 v[40:43], v[168:171], v[202:205], v[40:43]
	v_mfma_f32_16x16x32_bf16 v[36:39], v[176:179], v[202:205], v[36:39]
	v_mfma_f32_16x16x32_bf16 v[32:35], v[186:189], v[202:205], v[32:35]
	s_waitcnt lgkmcnt(2)
	v_mfma_f32_16x16x32_bf16 v[28:31], v[156:159], v[206:209], v[28:31]
	v_mfma_f32_16x16x32_bf16 v[24:27], v[164:167], v[206:209], v[24:27]
	v_mfma_f32_16x16x32_bf16 v[20:23], v[172:175], v[206:209], v[20:23]
	v_mfma_f32_16x16x32_bf16 v[16:19], v[180:183], v[206:209], v[16:19]
	v_mfma_f32_16x16x32_bf16 v[28:31], v[160:163], v[210:213], v[28:31]
	v_mfma_f32_16x16x32_bf16 v[24:27], v[168:171], v[210:213], v[24:27]
	v_mfma_f32_16x16x32_bf16 v[20:23], v[176:179], v[210:213], v[20:23]
	v_mfma_f32_16x16x32_bf16 v[16:19], v[186:189], v[210:213], v[16:19]
	s_waitcnt lgkmcnt(0)
	v_mfma_f32_16x16x32_bf16 v[12:15], v[156:159], v[214:217], v[12:15]
	v_mfma_f32_16x16x32_bf16 v[8:11], v[164:167], v[214:217], v[8:11]
	v_mfma_f32_16x16x32_bf16 v[4:7], v[172:175], v[214:217], v[4:7]
	v_mfma_f32_16x16x32_bf16 v[0:3], v[180:183], v[214:217], v[0:3]
	v_mfma_f32_16x16x32_bf16 v[12:15], v[160:163], v[218:221], v[12:15]
	v_mfma_f32_16x16x32_bf16 v[8:11], v[168:171], v[218:221], v[8:11]
	v_mfma_f32_16x16x32_bf16 v[4:7], v[176:179], v[218:221], v[4:7]
	v_mfma_f32_16x16x32_bf16 v[0:3], v[186:189], v[218:221], v[0:3]
	s_waitcnt vmcnt(0)
	s_barrier
	s_setprio 0
	s_add_i32 s61, s61, 2
	s_add_u32 s50, s50, 0x100
	s_addc_u32 s51, s51, 0
	s_add_u32 s41, s41, 0x100
	s_addc_u32 s43, s43, 0
	s_cmp_gt_u32 s61, 29
	s_cbranch_scc0 .Lmy_m64_0_w0_top
	s_add_i32 s58, s62, s3
	v_lshl_add_u64 v[222:223], v[222:223], 0, s[36:37]
	s_mov_b32 m0, s58
	s_nop 0
	global_load_lds_dwordx4 v[222:223], off
	v_lshl_add_u64 v[232:233], v[222:223], 0, v[234:235]
	s_bitset1_b32 m0, 12
	s_nop 0
	global_load_lds_dwordx4 v[232:233], off
	s_add_i32 m0, s58, 0x2000
	s_add_u32 s56, s56, 0x80080
	v_lshl_add_u64 v[222:223], v[224:225], 0, s[36:37]
	s_addc_u32 s57, s57, 0
	s_add_i32 s58, s63, s3
	global_load_lds_dwordx4 v[222:223], off
	v_lshl_add_u64 v[232:233], v[222:223], 0, v[234:235]
	s_bitset1_b32 m0, 12
	s_nop 0
	global_load_lds_dwordx4 v[232:233], off
	v_lshl_add_u64 v[222:223], s[56:57], 0, v[130:131]
	s_mov_b32 m0, s58
	s_nop 0
	global_load_lds_dwordx4 v[222:223], off
	v_lshl_add_u64 v[232:233], v[222:223], 0, v[234:235]
	s_bitset1_b32 m0, 12
	s_nop 0
	global_load_lds_dwordx4 v[232:233], off
	v_lshl_add_u64 v[222:223], s[56:57], 0, v[134:135]
	s_add_i32 m0, s58, 0x2000
	s_nop 0
	global_load_lds_dwordx4 v[222:223], off
	v_lshl_add_u64 v[232:233], v[222:223], 0, v[234:235]
	s_bitset1_b32 m0, 12
	s_nop 0
	global_load_lds_dwordx4 v[232:233], off
	v_lshl_add_u64 v[222:223], v[226:227], 0, s[36:37]
	s_mov_b32 m0, s44
	s_nop 0
	global_load_lds_dwordx4 v[222:223], off
	v_lshl_add_u64 v[232:233], v[222:223], 0, v[234:235]
	s_bitset1_b32 m0, 12
	s_nop 0
	global_load_lds_dwordx4 v[232:233], off
	v_lshl_add_u64 v[222:223], v[228:229], 0, s[36:37]
	s_mov_b32 m0, s45
	s_nop 0
	global_load_lds_dwordx4 v[222:223], off
	v_lshl_add_u64 v[232:233], v[222:223], 0, v[234:235]
	s_bitset1_b32 m0, 12
	s_nop 0
	global_load_lds_dwordx4 v[232:233], off
	s_branch .Lmy_m64_0_exit
.Lmy_m64_0_w1_entry:
	v_mov_b32_e32 v234, 0xfffe0000
	v_mov_b32_e32 v235, -1
.Lmy_m64_0_w1_top:
	ds_read_b128 v[156:159], v152
	ds_read_b128 v[160:163], v152 offset:1024
	ds_read_b128 v[164:167], v152 offset:2048
	ds_read_b128 v[168:171], v152 offset:3072
	ds_read_b128 v[172:175], v153
	ds_read_b128 v[176:179], v153 offset:1024
	ds_read_b128 v[180:183], v153 offset:2048
	ds_read_b128 v[186:189], v153 offset:3072
	s_add_u32 s56, s50, 0xfff80080
	s_addc_u32 s57, s51, -1
	s_cmp_eq_u32 s61, 28
	s_cselect_b32 s59, s4, s57
	s_cselect_b32 s58, s5, s56
	s_cselect_b32 s57, s12, s43
	s_cselect_b32 s56, s13, s41
	v_lshl_add_u64 v[222:223], s[50:51], 0, v[142:143]
	s_add_i32 m0, s6, 0xc000
	ds_read_b128 v[190:193], v154
	ds_read_b128 v[194:197], v154 offset:1024
	ds_read_b128 v[198:201], v154 offset:2048
	ds_read_b128 v[202:205], v154 offset:3072
	ds_read_b128 v[206:209], v154 offset:4096
	ds_read_b128 v[210:213], v154 offset:5120
	ds_read_b128 v[214:217], v154 offset:6144
	ds_read_b128 v[218:221], v154 offset:7168
	global_load_lds_dwordx4 v[222:223], off
	v_lshl_add_u64 v[232:233], v[222:223], 0, v[234:235]
	s_bitset0_b32 m0, 12
	s_nop 0
	global_load_lds_dwordx4 v[232:233], off
	v_lshl_add_u64 v[222:223], s[50:51], 0, v[144:145]
	s_add_i32 m0, s6, 0xe000
	s_nop 0
	global_load_lds_dwordx4 v[222:223], off
	v_lshl_add_u64 v[232:233], v[222:223], 0, v[234:235]
	s_bitset0_b32 m0, 12
	s_nop 0
	global_load_lds_dwordx4 v[232:233], off
	s_waitcnt lgkmcnt(0)
	s_setprio 1
	s_barrier
; #define PG8_STAGE(bufoff, gbase, voff) do { _Pragma("unroll") for (int _i = 0; _i < 2; ++_i) \
;         __builtin_amdgcn_global_load_lds((const unsigned*)((const char*)(gbase) + (voff)[_i]), (PG8_LAS unsigned*)(lds + (bufoff) + ldsw + _i * 8192), 16, 0, 0); } while (0)
; #define PG8_LDA(dst, b, h) do { _Pragma("unroll") for (int m = 0; m < 4; ++m) _Pragma("unroll") for (int k = 0; k < 2; ++k) dst[m][k] = *(const PG8_LAS bf16x8*)(lds + PG8_SA(b, h) + aoff + m * 2048 + k * 1024); } while (0)
; #define PG8_LDB(dst, b, h) do { _Pragma("unroll") for (int n = 0; n < 2; ++n) _Pragma("unroll") for (int k = 0; k < 2; ++k) dst[n][k] = *(const PG8_LAS bf16x8*)(lds + PG8_SB(b, h) + boff + n * 2048 + k * 1024); } while (0)
; #define PG8_MMA(ai, bj, At, Bt) do { __builtin_amdgcn_s_setprio(1); _Pragma("unroll") for (int m = 0; m < 4; ++m) _Pragma("unroll") for (int n = 0; n < 2; ++n) _Pragma("unroll") for (int k = 0; k < 2; ++k) \
;         acc[ai][bj][m][n] = __builtin_amdgcn_mfma_f32_16x16x32_bf16(Bt[n][k], At[m][k], acc[ai][bj][m][n], 0, 0, 0); __builtin_amdgcn_s_setprio(0); } while (0)
; template <class Epi, class Sched, bool ALIGN_EPI = false, bool SP2 = false>
; __device__ __forceinline__ void gemm_phase(PG8_LAS unsigned char* lds, const Gemm g, const Sched& S, const Epi& E) {
;     ...
;             if constexpr (SP2) {
;             PG8_LDB(B0, 0, 0); PG8_LDB(B1, 0, 1); PG8_SCHED; PG8_LDA(At, 0, 0); PG8_STAGE(PG8_SA(1, 1), a1 + hstepA, voffA);
;             PG8_WAIT_V(8); PG8_WAIT_L(0); PG8_BAR; PG8_MMA(0, 0, At, B0); PG8_MMA(0, 1, At, B1); PG8_BAR; PG8_SCHED;
;             PG8_LDA(At, 0, 1); PG8_STAGE(PG8_SB(0, 0), b2, voffB); PG8_STAGE(PG8_SB(0, 1), b2 + hstepB, voffB); PG8_STAGE(PG8_SA(0, 0), a2, voffA);
;             PG8_WAIT_V(8); PG8_WAIT_L(0); PG8_BAR; PG8_MMA(1, 0, At, B0); PG8_MMA(1, 1, At, B1); PG8_BAR; PG8_SCHED;
;             PG8_LDB(B0, 1, 0); PG8_LDB(B1, 1, 1); PG8_SCHED; PG8_LDA(At, 1, 0); PG8_STAGE(PG8_SA(0, 1), a2 + hstepA, voffA);
;             PG8_WAIT_V(8); PG8_WAIT_L(0); PG8_BAR; PG8_MMA(0, 0, At, B0); PG8_MMA(0, 1, At, B1); PG8_BAR; PG8_SCHED;
;             PG8_LDA(At, 1, 1); PG8_STAGE(PG8_SB(1, 0), b3, voffB); PG8_STAGE(PG8_SB(1, 1), b3 + hstepB, voffB); PG8_STAGE(PG8_SA(1, 0), a3, voffA);
;             PG8_WAIT_V(8); PG8_WAIT_L(0); PG8_BAR; PG8_MMA(1, 0, At, B0); PG8_MMA(1, 1, At, B1); PG8_BAR; PG8_SCHED;
	v_mfma_f32_16x16x32_bf16 v[124:127], v[156:159], v[190:193], v[124:127]
	v_mfma_f32_16x16x32_bf16 v[120:123], v[164:167], v[190:193], v[120:123]
	v_mfma_f32_16x16x32_bf16 v[116:119], v[172:175], v[190:193], v[116:119]
	v_mfma_f32_16x16x32_bf16 v[112:115], v[180:183], v[190:193], v[112:115]
	v_mfma_f32_16x16x32_bf16 v[124:127], v[160:163], v[194:197], v[124:127]
	v_mfma_f32_16x16x32_bf16 v[120:123], v[168:171], v[194:197], v[120:123]
	v_mfma_f32_16x16x32_bf16 v[116:119], v[176:179], v[194:197], v[116:119]
	v_mfma_f32_16x16x32_bf16 v[112:115], v[186:189], v[194:197], v[112:115]
	ds_read_b128 v[190:193], v154 offset:16384
	ds_read_b128 v[194:197], v154 offset:17408
	v_mfma_f32_16x16x32_bf16 v[108:111], v[156:159], v[198:201], v[108:111]
	v_mfma_f32_16x16x32_bf16 v[104:107], v[164:167], v[198:201], v[104:107]
	v_mfma_f32_16x16x32_bf16 v[100:103], v[172:175], v[198:201], v[100:103]
	v_mfma_f32_16x16x32_bf16 v[96:99], v[180:183], v[198:201], v[96:99]
	v_mfma_f32_16x16x32_bf16 v[108:111], v[160:163], v[202:205], v[108:111]
	v_mfma_f32_16x16x32_bf16 v[104:107], v[168:171], v[202:205], v[104:107]
	v_mfma_f32_16x16x32_bf16 v[100:103], v[176:179], v[202:205], v[100:103]
	v_mfma_f32_16x16x32_bf16 v[96:99], v[186:189], v[202:205], v[96:99]
	ds_read_b128 v[198:201], v154 offset:18432
	ds_read_b128 v[202:205], v154 offset:19456
	v_mfma_f32_16x16x32_bf16 v[92:95], v[156:159], v[206:209], v[92:95]
	v_mfma_f32_16x16x32_bf16 v[88:91], v[164:167], v[206:209], v[88:91]
	v_mfma_f32_16x16x32_bf16 v[84:87], v[172:175], v[206:209], v[84:87]
	v_mfma_f32_16x16x32_bf16 v[80:83], v[180:183], v[206:209], v[80:83]
	v_mfma_f32_16x16x32_bf16 v[92:95], v[160:163], v[210:213], v[92:95]
	v_mfma_f32_16x16x32_bf16 v[88:91], v[168:171], v[210:213], v[88:91]
	v_mfma_f32_16x16x32_bf16 v[84:87], v[176:179], v[210:213], v[84:87]
	v_mfma_f32_16x16x32_bf16 v[80:83], v[186:189], v[210:213], v[80:83]
	ds_read_b128 v[206:209], v154 offset:20480
	ds_read_b128 v[210:213], v154 offset:21504
	v_mfma_f32_16x16x32_bf16 v[76:79], v[156:159], v[214:217], v[76:79]
	v_mfma_f32_16x16x32_bf16 v[72:75], v[164:167], v[214:217], v[72:75]
	v_mfma_f32_16x16x32_bf16 v[68:71], v[172:175], v[214:217], v[68:71]
	v_mfma_f32_16x16x32_bf16 v[64:67], v[180:183], v[214:217], v[64:67]
	v_mfma_f32_16x16x32_bf16 v[76:79], v[160:163], v[218:221], v[76:79]
	v_mfma_f32_16x16x32_bf16 v[72:75], v[168:171], v[218:221], v[72:75]
	v_mfma_f32_16x16x32_bf16 v[68:71], v[176:179], v[218:221], v[68:71]
	v_mfma_f32_16x16x32_bf16 v[64:67], v[186:189], v[218:221], v[64:67]
	ds_read_b128 v[214:217], v154 offset:22528
	ds_read_b128 v[218:221], v154 offset:23552
	s_waitcnt lgkmcnt(6)
	v_mfma_f32_16x16x32_bf16 v[60:63], v[156:159], v[190:193], v[60:63]
	v_mfma_f32_16x16x32_bf16 v[56:59], v[164:167], v[190:193], v[56:59]
	v_mfma_f32_16x16x32_bf16 v[52:55], v[172:175], v[190:193], v[52:55]
	v_mfma_f32_16x16x32_bf16 v[48:51], v[180:183], v[190:193], v[48:51]
	v_mfma_f32_16x16x32_bf16 v[60:63], v[160:163], v[194:197], v[60:63]
	v_mfma_f32_16x16x32_bf16 v[56:59], v[168:171], v[194:197], v[56:59]
	v_mfma_f32_16x16x32_bf16 v[52:55], v[176:179], v[194:197], v[52:55]
	v_mfma_f32_16x16x32_bf16 v[48:51], v[186:189], v[194:197], v[48:51]
	s_waitcnt lgkmcnt(4)
	v_mfma_f32_16x16x32_bf16 v[44:47], v[156:159], v[198:201], v[44:47]
	v_mfma_f32_16x16x32_bf16 v[40:43], v[164:167], v[198:201], v[40:43]
	v_mfma_f32_16x16x32_bf16 v[36:39], v[172:175], v[198:201], v[36:39]
	v_mfma_f32_16x16x32_bf16 v[32:35], v[180:183], v[198:201], v[32:35]
	v_mfma_f32_16x16x32_bf16 v[44:47], v[160:163], v[202:205], v[44:47]
	v_mfma_f32_16x16x32_bf16 v[40:43], v[168:171], v[202:205], v[40:43]
	v_mfma_f32_16x16x32_bf16 v[36:39], v[176:179], v[202:205], v[36:39]
	v_mfma_f32_16x16x32_bf16 v[32:35], v[186:189], v[202:205], v[32:35]
	s_waitcnt lgkmcnt(2)
	v_mfma_f32_16x16x32_bf16 v[28:31], v[156:159], v[206:209], v[28:31]
	v_mfma_f32_16x16x32_bf16 v[24:27], v[164:167], v[206:209], v[24:27]
	v_mfma_f32_16x16x32_bf16 v[20:23], v[172:175], v[206:209], v[20:23]
	v_mfma_f32_16x16x32_bf16 v[16:19], v[180:183], v[206:209], v[16:19]
	v_mfma_f32_16x16x32_bf16 v[28:31], v[160:163], v[210:213], v[28:31]
	v_mfma_f32_16x16x32_bf16 v[24:27], v[168:171], v[210:213], v[24:27]
	v_mfma_f32_16x16x32_bf16 v[20:23], v[176:179], v[210:213], v[20:23]
	v_mfma_f32_16x16x32_bf16 v[16:19], v[186:189], v[210:213], v[16:19]
	s_waitcnt lgkmcnt(0)
	v_mfma_f32_16x16x32_bf16 v[12:15], v[156:159], v[214:217], v[12:15]
	v_mfma_f32_16x16x32_bf16 v[8:11], v[164:167], v[214:217], v[8:11]
	v_mfma_f32_16x16x32_bf16 v[4:7], v[172:175], v[214:217], v[4:7]
	v_mfma_f32_16x16x32_bf16 v[0:3], v[180:183], v[214:217], v[0:3]
	v_mfma_f32_16x16x32_bf16 v[12:15], v[160:163], v[218:221], v[12:15]
	v_mfma_f32_16x16x32_bf16 v[8:11], v[168:171], v[218:221], v[8:11]
	v_mfma_f32_16x16x32_bf16 v[4:7], v[176:179], v[218:221], v[4:7]
	v_mfma_f32_16x16x32_bf16 v[0:3], v[186:189], v[218:221], v[0:3]
	s_waitcnt vmcnt(0)
	s_barrier
	s_setprio 0
	s_add_i32 s62, 0, 0x18000
	v_add_u32_e32 v155, s62, v150
	s_add_i32 s63, 0, 0x1c000
	ds_read_b128 v[156:159], v155
	ds_read_b128 v[160:163], v155 offset:1024
	ds_read_b128 v[164:167], v155 offset:2048
	ds_read_b128 v[168:171], v155 offset:3072
	v_add_u32_e32 v155, s63, v150
	ds_read_b128 v[172:175], v155
	ds_read_b128 v[176:179], v155 offset:1024
	ds_read_b128 v[180:183], v155 offset:2048
	ds_read_b128 v[186:189], v155 offset:3072
	s_add_u32 s58, s58, 0x80000
	s_addc_u32 s59, s59, 0
	s_mov_b32 m0, s8
	v_lshl_add_u64 v[230:231], s[58:59], 0, v[128:129]
	ds_read_b128 v[190:193], v154 offset:32768
	ds_read_b128 v[194:197], v154 offset:33792
	ds_read_b128 v[198:201], v154 offset:34816
	ds_read_b128 v[202:205], v154 offset:35840
	ds_read_b128 v[206:209], v154 offset:36864
	ds_read_b128 v[210:213], v154 offset:37888
	ds_read_b128 v[214:217], v154 offset:38912
	ds_read_b128 v[218:221], v154 offset:39936
	global_load_lds_dwordx4 v[230:231], off
	v_lshl_add_u64 v[232:233], v[230:231], 0, v[234:235]
	s_bitset0_b32 m0, 12
	s_nop 0
	global_load_lds_dwordx4 v[232:233], off
	v_lshl_add_u64 v[230:231], s[58:59], 0, v[132:133]
	s_mov_b32 m0, s9
	s_nop 0
	global_load_lds_dwordx4 v[230:231], off
	v_lshl_add_u64 v[232:233], v[230:231], 0, v[234:235]
	s_bitset0_b32 m0, 12
	s_nop 0
	global_load_lds_dwordx4 v[232:233], off
	s_waitcnt lgkmcnt(0)
	s_setprio 1
	s_barrier
; #define PG8_STAGE(bufoff, gbase, voff) do { _Pragma("unroll") for (int _i = 0; _i < 2; ++_i) \
;         __builtin_amdgcn_global_load_lds((const unsigned*)((const char*)(gbase) + (voff)[_i]), (PG8_LAS unsigned*)(lds + (bufoff) + ldsw + _i * 8192), 16, 0, 0); } while (0)
; #define PG8_LDA(dst, b, h) do { _Pragma("unroll") for (int m = 0; m < 4; ++m) _Pragma("unroll") for (int k = 0; k < 2; ++k) dst[m][k] = *(const PG8_LAS bf16x8*)(lds + PG8_SA(b, h) + aoff + m * 2048 + k * 1024); } while (0)
; #define PG8_LDB(dst, b, h) do { _Pragma("unroll") for (int n = 0; n < 2; ++n) _Pragma("unroll") for (int k = 0; k < 2; ++k) dst[n][k] = *(const PG8_LAS bf16x8*)(lds + PG8_SB(b, h) + boff + n * 2048 + k * 1024); } while (0)
; #define PG8_MMA(ai, bj, At, Bt) do { __builtin_amdgcn_s_setprio(1); _Pragma("unroll") for (int m = 0; m < 4; ++m) _Pragma("unroll") for (int n = 0; n < 2; ++n) _Pragma("unroll") for (int k = 0; k < 2; ++k) \
;         acc[ai][bj][m][n] = __builtin_amdgcn_mfma_f32_16x16x32_bf16(Bt[n][k], At[m][k], acc[ai][bj][m][n], 0, 0, 0); __builtin_amdgcn_s_setprio(0); } while (0)
; #define PG8_WAIT_V(n) asm volatile("s_waitcnt vmcnt(" #n ")" ::: "memory")
; #define PG8_WAIT_L(n) asm volatile("s_waitcnt lgkmcnt(" #n ")" ::: "memory")
; #define PG8_BAR __builtin_amdgcn_s_barrier()
; #define PG8_SCHED __builtin_amdgcn_sched_barrier(0)
; template <class Epi, class Sched, bool ALIGN_EPI = false, bool SP2 = false>
; __device__ __forceinline__ void gemm_phase(PG8_LAS unsigned char* lds, const Gemm g, const Sched& S, const Epi& E) {
;     ...
;             PG8_LDB(B0, 1, 0); PG8_LDB(B1, 1, 1); PG8_SCHED; PG8_LDA(At, 1, 0); PG8_STAGE(PG8_SA(0, 1), a2 + hstepA, voffA);
;             PG8_WAIT_V(8); PG8_WAIT_L(0); PG8_BAR; PG8_MMA(0, 0, At, B0); PG8_MMA(0, 1, At, B1); PG8_BAR; PG8_SCHED;
;             PG8_LDA(At, 1, 1); PG8_STAGE(PG8_SB(1, 0), b3, voffB); PG8_STAGE(PG8_SB(1, 1), b3 + hstepB, voffB); PG8_STAGE(PG8_SA(1, 0), a3, voffA);
;             PG8_WAIT_V(8); PG8_WAIT_L(0); PG8_BAR; PG8_MMA(1, 0, At, B0); PG8_MMA(1, 1, At, B1); PG8_BAR; PG8_SCHED;
	v_mfma_f32_16x16x32_bf16 v[124:127], v[156:159], v[190:193], v[124:127]
	v_mfma_f32_16x16x32_bf16 v[120:123], v[164:167], v[190:193], v[120:123]
	v_mfma_f32_16x16x32_bf16 v[116:119], v[172:175], v[190:193], v[116:119]
	v_mfma_f32_16x16x32_bf16 v[112:115], v[180:183], v[190:193], v[112:115]
	v_mfma_f32_16x16x32_bf16 v[124:127], v[160:163], v[194:197], v[124:127]
	v_mfma_f32_16x16x32_bf16 v[120:123], v[168:171], v[194:197], v[120:123]
	v_mfma_f32_16x16x32_bf16 v[116:119], v[176:179], v[194:197], v[116:119]
	v_mfma_f32_16x16x32_bf16 v[112:115], v[186:189], v[194:197], v[112:115]
	ds_read_b128 v[190:193], v154 offset:49152
	ds_read_b128 v[194:197], v154 offset:50176
	v_mfma_f32_16x16x32_bf16 v[108:111], v[156:159], v[198:201], v[108:111]
	v_mfma_f32_16x16x32_bf16 v[104:107], v[164:167], v[198:201], v[104:107]
	v_mfma_f32_16x16x32_bf16 v[100:103], v[172:175], v[198:201], v[100:103]
	v_mfma_f32_16x16x32_bf16 v[96:99], v[180:183], v[198:201], v[96:99]
	v_mfma_f32_16x16x32_bf16 v[108:111], v[160:163], v[202:205], v[108:111]
	v_mfma_f32_16x16x32_bf16 v[104:107], v[168:171], v[202:205], v[104:107]
	v_mfma_f32_16x16x32_bf16 v[100:103], v[176:179], v[202:205], v[100:103]
	v_mfma_f32_16x16x32_bf16 v[96:99], v[186:189], v[202:205], v[96:99]
	ds_read_b128 v[198:201], v154 offset:51200
	ds_read_b128 v[202:205], v154 offset:52224
	v_mfma_f32_16x16x32_bf16 v[92:95], v[156:159], v[206:209], v[92:95]
	v_mfma_f32_16x16x32_bf16 v[88:91], v[164:167], v[206:209], v[88:91]
	v_mfma_f32_16x16x32_bf16 v[84:87], v[172:175], v[206:209], v[84:87]
	v_mfma_f32_16x16x32_bf16 v[80:83], v[180:183], v[206:209], v[80:83]
	v_mfma_f32_16x16x32_bf16 v[92:95], v[160:163], v[210:213], v[92:95]
	v_mfma_f32_16x16x32_bf16 v[88:91], v[168:171], v[210:213], v[88:91]
	v_mfma_f32_16x16x32_bf16 v[84:87], v[176:179], v[210:213], v[84:87]
	v_mfma_f32_16x16x32_bf16 v[80:83], v[186:189], v[210:213], v[80:83]
	ds_read_b128 v[206:209], v154 offset:53248
	ds_read_b128 v[210:213], v154 offset:54272
	v_mfma_f32_16x16x32_bf16 v[76:79], v[156:159], v[214:217], v[76:79]
	v_mfma_f32_16x16x32_bf16 v[72:75], v[164:167], v[214:217], v[72:75]
	v_mfma_f32_16x16x32_bf16 v[68:71], v[172:175], v[214:217], v[68:71]
	v_mfma_f32_16x16x32_bf16 v[64:67], v[180:183], v[214:217], v[64:67]
	v_mfma_f32_16x16x32_bf16 v[76:79], v[160:163], v[218:221], v[76:79]
	v_mfma_f32_16x16x32_bf16 v[72:75], v[168:171], v[218:221], v[72:75]
	v_mfma_f32_16x16x32_bf16 v[68:71], v[176:179], v[218:221], v[68:71]
	v_mfma_f32_16x16x32_bf16 v[64:67], v[186:189], v[218:221], v[64:67]
	ds_read_b128 v[214:217], v154 offset:55296
	ds_read_b128 v[218:221], v154 offset:56320
	s_waitcnt lgkmcnt(6)
	v_mfma_f32_16x16x32_bf16 v[60:63], v[156:159], v[190:193], v[60:63]
	v_mfma_f32_16x16x32_bf16 v[56:59], v[164:167], v[190:193], v[56:59]
	v_mfma_f32_16x16x32_bf16 v[52:55], v[172:175], v[190:193], v[52:55]
	v_mfma_f32_16x16x32_bf16 v[48:51], v[180:183], v[190:193], v[48:51]
	v_mfma_f32_16x16x32_bf16 v[60:63], v[160:163], v[194:197], v[60:63]
	v_mfma_f32_16x16x32_bf16 v[56:59], v[168:171], v[194:197], v[56:59]
	v_mfma_f32_16x16x32_bf16 v[52:55], v[176:179], v[194:197], v[52:55]
	v_mfma_f32_16x16x32_bf16 v[48:51], v[186:189], v[194:197], v[48:51]
	s_waitcnt lgkmcnt(4)
	v_mfma_f32_16x16x32_bf16 v[44:47], v[156:159], v[198:201], v[44:47]
	v_mfma_f32_16x16x32_bf16 v[40:43], v[164:167], v[198:201], v[40:43]
	v_mfma_f32_16x16x32_bf16 v[36:39], v[172:175], v[198:201], v[36:39]
	v_mfma_f32_16x16x32_bf16 v[32:35], v[180:183], v[198:201], v[32:35]
	v_mfma_f32_16x16x32_bf16 v[44:47], v[160:163], v[202:205], v[44:47]
	v_mfma_f32_16x16x32_bf16 v[40:43], v[168:171], v[202:205], v[40:43]
	v_mfma_f32_16x16x32_bf16 v[36:39], v[176:179], v[202:205], v[36:39]
	v_mfma_f32_16x16x32_bf16 v[32:35], v[186:189], v[202:205], v[32:35]
	s_waitcnt lgkmcnt(2)
	v_mfma_f32_16x16x32_bf16 v[28:31], v[156:159], v[206:209], v[28:31]
	v_mfma_f32_16x16x32_bf16 v[24:27], v[164:167], v[206:209], v[24:27]
	v_mfma_f32_16x16x32_bf16 v[20:23], v[172:175], v[206:209], v[20:23]
	v_mfma_f32_16x16x32_bf16 v[16:19], v[180:183], v[206:209], v[16:19]
	v_mfma_f32_16x16x32_bf16 v[28:31], v[160:163], v[210:213], v[28:31]
	v_mfma_f32_16x16x32_bf16 v[24:27], v[168:171], v[210:213], v[24:27]
	v_mfma_f32_16x16x32_bf16 v[20:23], v[176:179], v[210:213], v[20:23]
	v_mfma_f32_16x16x32_bf16 v[16:19], v[186:189], v[210:213], v[16:19]
	s_waitcnt lgkmcnt(0)
	v_mfma_f32_16x16x32_bf16 v[12:15], v[156:159], v[214:217], v[12:15]
	v_mfma_f32_16x16x32_bf16 v[8:11], v[164:167], v[214:217], v[8:11]
	v_mfma_f32_16x16x32_bf16 v[4:7], v[172:175], v[214:217], v[4:7]
	v_mfma_f32_16x16x32_bf16 v[0:3], v[180:183], v[214:217], v[0:3]
	v_mfma_f32_16x16x32_bf16 v[12:15], v[160:163], v[218:221], v[12:15]
	v_mfma_f32_16x16x32_bf16 v[8:11], v[168:171], v[218:221], v[8:11]
	v_mfma_f32_16x16x32_bf16 v[4:7], v[176:179], v[218:221], v[4:7]
	v_mfma_f32_16x16x32_bf16 v[0:3], v[186:189], v[218:221], v[0:3]
	s_waitcnt vmcnt(0)
	s_barrier
	s_setprio 0
	s_add_i32 s61, s61, 2
	s_add_u32 s50, s50, 0x100
	s_addc_u32 s51, s51, 0
	s_add_u32 s41, s41, 0x100
	s_addc_u32 s43, s43, 0
	s_cmp_gt_u32 s61, 29
	s_cbranch_scc0 .Lmy_m64_0_w1_top
